# v4: V-fragment LDS reads as pairs of ds_read_b64 (64-bank, conflict-free) instead of ds_read2_b64; address constants folded into ds offsets
# speedup vs baseline: 1.0194x; 1.0120x over previous
; template <int MODE>
; DI void attn_item(const Params& p, int item, char* smem, u16* gdst) {
;     ...
;         for (int s2 = 0; s2 < 2; ++s2) {
;           u32x4 pk;
;           pk[0] = cvtpk(s[qt][2 * s2][0], s[qt][2 * s2][1]);
;           pk[1] = cvtpk(s[qt][2 * s2][2], s[qt][2 * s2][3]);
;           pk[2] = cvtpk(s[qt][2 * s2 + 1][0], s[qt][2 * s2 + 1][1]);
;           pk[3] = cvtpk(s[qt][2 * s2 + 1][2], s[qt][2 * s2 + 1][3]);
;           pf[qt][s2] = __builtin_bit_cast(bf16x8, pk);
;         }
;       }
; #pragma unroll
;       for (int dt = 0; dt < 8; ++dt) {
; #pragma unroll
;         for (int s2 = 0; s2 < 2; ++s2) {
;           const u16* vp = sV + (dt * 16 + fr) * VSTR + fq * 4;
;           u32x2 v0 = *(const u32x2*)(vp + (2 * s2) * 16);
;           u32x2 v1 = *(const u32x2*)(vp + (2 * s2 + 1) * 16);
;           u32x4 vv = {v0[0], v0[1], v1[0], v1[1]};
;           bf16x8 vf = __builtin_bit_cast(bf16x8, vv);
;           o[0][dt] = __builtin_amdgcn_mfma_f32_16x16x32_bf16(vf, pf[0][s2], o[0][dt], 0, 0, 0);
;           o[1][dt] = __builtin_amdgcn_mfma_f32_16x16x32_bf16(vf, pf[1][s2], o[1][dt], 0, 0, 0);
;         }
;       }
.LBB0_1586:
	v_cvt_pk_bf16_f32 v122, v132, v133
	v_cvt_pk_bf16_f32 v123, v134, v135
	v_add3_u32 v133, s60, v190, v202
	ds_read_b64 v[232:233], v133 offset:24576
	ds_read_b64 v[234:235], v133 offset:24608
	ds_read_b64 v[236:237], v133 offset:24640
	ds_read_b64 v[238:239], v133 offset:24672
	ds_read_b64 v[240:241], v133 offset:26880
	ds_read_b64 v[242:243], v133 offset:26912
	ds_read_b64 v[244:245], v133 offset:26944
	ds_read_b64 v[246:247], v133 offset:26976
	ds_read_b64 v[248:249], v133 offset:29184
	ds_read_b64 v[250:251], v133 offset:29216
	ds_read_b64 v[252:253], v133 offset:29248
	ds_read_b64 v[254:255], v133 offset:29280
	v_cvt_pk_bf16_f32 v120, v128, v129
	v_cvt_pk_bf16_f32 v121, v130, v131
	v_add_f32_e32 v124, v205, v214
	v_cndmask_b32_e64 v205, v124, v213, s[4:5]
	v_add_f32_e32 v124, v207, v210
	v_cndmask_b32_e64 v207, v124, v209, s[4:5]
	v_cvt_pk_bf16_f32 v124, v164, v147
	v_cvt_pk_bf16_f32 v125, v170, v157
	v_cvt_pk_bf16_f32 v126, v116, v117
	v_cvt_pk_bf16_f32 v127, v118, v119
	s_waitcnt lgkmcnt(10)
	v_mfma_f32_16x16x32_bf16 v[92:95], v[232:235], v[120:123], v[92:95]
	v_add_f32_e32 v215, v112, v113
	v_cvt_pk_bf16_f32 v112, v136, v137
	v_cvt_pk_bf16_f32 v113, v138, v139
	v_mfma_f32_16x16x32_bf16 v[28:31], v[232:235], v[124:127], v[28:31]
	ds_read_b64 v[232:233], v133 offset:31488
	ds_read_b64 v[234:235], v133 offset:31520
	v_cvt_pk_bf16_f32 v114, v140, v141
	v_cvt_pk_bf16_f32 v115, v142, v143
	v_cvt_pk_bf16_f32 v116, v172, v165
	v_cvt_pk_bf16_f32 v117, v174, v167
	v_cvt_pk_bf16_f32 v118, v176, v169
	v_cvt_pk_bf16_f32 v119, v178, v171
	v_add_f32_e32 v132, v211, v212
	v_fmac_f32_e32 v215, v183, v166
	v_fmac_f32_e32 v132, v208, v168
	s_waitcnt lgkmcnt(10)
	v_mfma_f32_16x16x32_bf16 v[92:95], v[236:239], v[112:115], v[92:95]
	v_mov_b32_e32 v208, v132
	v_mov_b32_e32 v183, v215
	v_mfma_f32_16x16x32_bf16 v[28:31], v[236:239], v[116:119], v[28:31]
	ds_read_b64 v[236:237], v133 offset:31552
	ds_read_b64 v[238:239], v133 offset:31584
	s_waitcnt lgkmcnt(10)
	v_mfma_f32_16x16x32_bf16 v[88:91], v[240:243], v[120:123], v[88:91]
	v_mfma_f32_16x16x32_bf16 v[24:27], v[240:243], v[124:127], v[24:27]
	ds_read_b64 v[240:241], v133 offset:33792
	ds_read_b64 v[242:243], v133 offset:33824
	s_waitcnt lgkmcnt(10)
	v_mfma_f32_16x16x32_bf16 v[88:91], v[244:247], v[112:115], v[88:91]
	v_mfma_f32_16x16x32_bf16 v[24:27], v[244:247], v[116:119], v[24:27]
	ds_read_b64 v[244:245], v133 offset:33856
	ds_read_b64 v[246:247], v133 offset:33888
	s_waitcnt lgkmcnt(10)
	v_mfma_f32_16x16x32_bf16 v[84:87], v[248:251], v[120:123], v[84:87]
	v_mfma_f32_16x16x32_bf16 v[20:23], v[248:251], v[124:127], v[20:23]
	ds_read_b64 v[248:249], v133 offset:36096
	ds_read_b64 v[250:251], v133 offset:36128
	s_waitcnt lgkmcnt(10)
	v_mfma_f32_16x16x32_bf16 v[84:87], v[252:255], v[112:115], v[84:87]
	v_mfma_f32_16x16x32_bf16 v[20:23], v[252:255], v[116:119], v[20:23]
	ds_read_b64 v[252:253], v133 offset:36160
	ds_read_b64 v[254:255], v133 offset:36192
	s_waitcnt lgkmcnt(10)
	v_mfma_f32_16x16x32_bf16 v[80:83], v[232:235], v[120:123], v[80:83]
	v_mfma_f32_16x16x32_bf16 v[16:19], v[232:235], v[124:127], v[16:19]
	ds_read_b64 v[232:233], v133 offset:38400
	ds_read_b64 v[234:235], v133 offset:38432
	s_waitcnt lgkmcnt(10)
	v_mfma_f32_16x16x32_bf16 v[80:83], v[236:239], v[112:115], v[80:83]
	v_mfma_f32_16x16x32_bf16 v[16:19], v[236:239], v[116:119], v[16:19]
	ds_read_b64 v[236:237], v133 offset:38464
	ds_read_b64 v[238:239], v133 offset:38496
	s_waitcnt lgkmcnt(10)
	v_mfma_f32_16x16x32_bf16 v[48:51], v[240:243], v[120:123], v[48:51]
	v_mfma_f32_16x16x32_bf16 v[12:15], v[240:243], v[124:127], v[12:15]
	ds_read_b64 v[240:241], v133 offset:40704
	ds_read_b64 v[242:243], v133 offset:40736
	s_waitcnt lgkmcnt(10)
	v_mfma_f32_16x16x32_bf16 v[48:51], v[244:247], v[112:115], v[48:51]
	v_mfma_f32_16x16x32_bf16 v[12:15], v[244:247], v[116:119], v[12:15]
	ds_read_b64 v[244:245], v133 offset:40768
	ds_read_b64 v[246:247], v133 offset:40800
	s_waitcnt lgkmcnt(10)
	v_mfma_f32_16x16x32_bf16 v[40:43], v[248:251], v[120:123], v[40:43]
	v_mfma_f32_16x16x32_bf16 v[8:11], v[248:251], v[124:127], v[8:11]
	s_waitcnt lgkmcnt(8)
	v_mfma_f32_16x16x32_bf16 v[40:43], v[252:255], v[112:115], v[40:43]
	v_mfma_f32_16x16x32_bf16 v[8:11], v[252:255], v[116:119], v[8:11]
	s_waitcnt lgkmcnt(6)
	v_mfma_f32_16x16x32_bf16 v[36:39], v[232:235], v[120:123], v[36:39]
	v_mfma_f32_16x16x32_bf16 v[4:7], v[232:235], v[124:127], v[4:7]
	s_waitcnt lgkmcnt(4)
	v_mfma_f32_16x16x32_bf16 v[36:39], v[236:239], v[112:115], v[36:39]
	v_mfma_f32_16x16x32_bf16 v[4:7], v[236:239], v[116:119], v[4:7]
	s_waitcnt lgkmcnt(2)
	v_mfma_f32_16x16x32_bf16 v[32:35], v[240:243], v[120:123], v[32:35]
	v_mfma_f32_16x16x32_bf16 v[0:3], v[240:243], v[124:127], v[0:3]
	s_waitcnt lgkmcnt(0)
	v_mfma_f32_16x16x32_bf16 v[32:35], v[244:247], v[112:115], v[32:35]
	v_mfma_f32_16x16x32_bf16 v[0:3], v[244:247], v[116:119], v[0:3]
	s_or_b64 exec, exec, s[16:17]
	s_cmp_eq_u32 s21, s51
	s_cbranch_scc1 .LBB0_1588

; template <int MODE>
; DI void attn_item(const Params& p, int item, char* smem, u16* gdst) {
;     ...
;         for (int s2 = 0; s2 < 2; ++s2) {
;           u32x4 pk;
;           pk[0] = cvtpk(s[qt][2 * s2][0], s[qt][2 * s2][1]);
;           pk[1] = cvtpk(s[qt][2 * s2][2], s[qt][2 * s2][3]);
;           pk[2] = cvtpk(s[qt][2 * s2 + 1][0], s[qt][2 * s2 + 1][1]);
;           pk[3] = cvtpk(s[qt][2 * s2 + 1][2], s[qt][2 * s2 + 1][3]);
;           pf[qt][s2] = __builtin_bit_cast(bf16x8, pk);
;         }
;       }
; #pragma unroll
;       for (int dt = 0; dt < 8; ++dt) {
; #pragma unroll
;         for (int s2 = 0; s2 < 2; ++s2) {
;           const u16* vp = sV + (dt * 16 + fr) * VSTR + fq * 4;
;           u32x2 v0 = *(const u32x2*)(vp + (2 * s2) * 16);
;           u32x2 v1 = *(const u32x2*)(vp + (2 * s2 + 1) * 16);
;           u32x4 vv = {v0[0], v0[1], v1[0], v1[1]};
;           bf16x8 vf = __builtin_bit_cast(bf16x8, vv);
;           o[0][dt] = __builtin_amdgcn_mfma_f32_16x16x32_bf16(vf, pf[0][s2], o[0][dt], 0, 0, 0);
;           o[1][dt] = __builtin_amdgcn_mfma_f32_16x16x32_bf16(vf, pf[1][s2], o[1][dt], 0, 0, 0);
;         }
;       }
.LBB0_1813:
	v_add_u32_e32 v150, s36, v198
	v_add_u32_e32 v150, 0x6000, v150
	v_add_u32_e32 v151, v150, v192
	v_add_u32_e32 v236, v150, v193
	ds_read_b64 v[232:233], v236
	ds_read_b64 v[234:235], v236 offset:32
	ds_read_b64 v[238:239], v236 offset:96
	ds_read_b64 v[236:237], v236 offset:64
	ds_read_b64 v[240:241], v151
	ds_read_b64 v[242:243], v151 offset:32
	ds_read_b64 v[244:245], v151 offset:64
	ds_read_b64 v[246:247], v151 offset:96
	v_add_u32_e32 v252, v150, v196
	ds_read_b64 v[248:249], v252
	ds_read_b64 v[250:251], v252 offset:32
	ds_read_b64 v[254:255], v252 offset:96
	ds_read_b64 v[252:253], v252 offset:64
	v_cvt_pk_bf16_f32 v210, v210, v211
	v_cvt_pk_bf16_f32 v211, v212, v155
	v_cvt_pk_bf16_f32 v212, v156, v157
	v_cvt_pk_bf16_f32 v156, v215, v216
	v_cvt_pk_bf16_f32 v215, v138, v139
	v_cvt_pk_bf16_f32 v139, v142, v143
	v_cvt_pk_bf16_f32 v216, v140, v141
	v_cvt_pk_bf16_f32 v140, v146, v147
	v_cvt_pk_bf16_f32 v138, v144, v145
	v_cvt_pk_bf16_f32 v213, v213, v214
	v_cvt_pk_bf16_f32 v214, v165, v167
	v_cvt_pk_bf16_f32 v217, v166, v217
	s_waitcnt lgkmcnt(10)
	v_mfma_f32_16x16x32_bf16 v[128:131], v[232:235], v[210:213], v[128:131]
	v_cvt_pk_bf16_f32 v157, v162, v163
	v_cvt_pk_bf16_f32 v158, v158, v159
	v_cvt_pk_bf16_f32 v159, v160, v161
	v_mfma_f32_16x16x32_bf16 v[96:99], v[232:235], v[214:217], v[96:99]
	v_cvt_pk_bf16_f32 v141, v148, v149
	s_waitcnt lgkmcnt(8)
	v_mfma_f32_16x16x32_bf16 v[128:131], v[236:239], v[156:159], v[128:131]
	v_add_f32_e32 v136, v136, v137
	v_add_f32_e32 v137, v153, v154
	v_fmac_f32_e32 v136, v202, v152
	v_fmac_f32_e32 v137, v204, v0
	v_mfma_f32_16x16x32_bf16 v[96:99], v[236:239], v[138:141], v[96:99]
	v_add_u32_e32 v236, v150, v197
	ds_read_b64 v[232:233], v236
	ds_read_b64 v[234:235], v236 offset:32
	ds_read_b64 v[238:239], v236 offset:96
	ds_read_b64 v[236:237], v236 offset:64
	v_add_f32_e32 v203, v203, v164
	v_add_f32_e32 v201, v201, v209
	v_mov_b32_e32 v204, v137
	v_mov_b32_e32 v202, v136
	s_waitcnt lgkmcnt(10)
	v_mfma_f32_16x16x32_bf16 v[124:127], v[240:243], v[210:213], v[124:127]
	v_mfma_f32_16x16x32_bf16 v[92:95], v[240:243], v[214:217], v[92:95]
	s_waitcnt lgkmcnt(8)
	v_mfma_f32_16x16x32_bf16 v[124:127], v[244:247], v[156:159], v[124:127]
	v_mfma_f32_16x16x32_bf16 v[92:95], v[244:247], v[138:141], v[92:95]
	ds_read_b64 v[240:241], v151 offset:9216
	ds_read_b64 v[242:243], v151 offset:9248
	ds_read_b64 v[244:245], v151 offset:9280
	ds_read_b64 v[246:247], v151 offset:9312
	s_waitcnt lgkmcnt(10)
	v_mfma_f32_16x16x32_bf16 v[132:135], v[248:251], v[210:213], v[132:135]
	v_mfma_f32_16x16x32_bf16 v[100:103], v[248:251], v[214:217], v[100:103]
	s_waitcnt lgkmcnt(8)
	v_mfma_f32_16x16x32_bf16 v[132:135], v[252:255], v[156:159], v[132:135]
	v_mfma_f32_16x16x32_bf16 v[100:103], v[252:255], v[138:141], v[100:103]
	ds_read_b64 v[248:249], v151 offset:11520
	ds_read_b64 v[250:251], v151 offset:11552
	ds_read_b64 v[252:253], v151 offset:11584
	ds_read_b64 v[254:255], v151 offset:11616
	s_waitcnt lgkmcnt(10)
	v_mfma_f32_16x16x32_bf16 v[120:123], v[232:235], v[210:213], v[120:123]
	v_mfma_f32_16x16x32_bf16 v[88:91], v[232:235], v[214:217], v[88:91]
	s_waitcnt lgkmcnt(8)
	v_mfma_f32_16x16x32_bf16 v[120:123], v[236:239], v[156:159], v[120:123]
	v_mfma_f32_16x16x32_bf16 v[88:91], v[236:239], v[138:141], v[88:91]
	ds_read_b64 v[232:233], v151 offset:13824
	ds_read_b64 v[234:235], v151 offset:13856
	ds_read_b64 v[236:237], v151 offset:13888
	ds_read_b64 v[238:239], v151 offset:13920
	s_waitcnt lgkmcnt(10)
	v_mfma_f32_16x16x32_bf16 v[104:107], v[240:243], v[210:213], v[104:107]
	v_mfma_f32_16x16x32_bf16 v[72:75], v[240:243], v[214:217], v[72:75]
	s_waitcnt lgkmcnt(8)
	v_mfma_f32_16x16x32_bf16 v[104:107], v[244:247], v[156:159], v[104:107]
	v_mfma_f32_16x16x32_bf16 v[72:75], v[244:247], v[138:141], v[72:75]
	ds_read_b64 v[240:241], v151 offset:16128
	ds_read_b64 v[242:243], v151 offset:16160
	ds_read_b64 v[244:245], v151 offset:16192
	ds_read_b64 v[246:247], v151 offset:16224
	s_waitcnt lgkmcnt(10)
	v_mfma_f32_16x16x32_bf16 v[108:111], v[248:251], v[210:213], v[108:111]
	v_mfma_f32_16x16x32_bf16 v[76:79], v[248:251], v[214:217], v[76:79]
	s_waitcnt lgkmcnt(8)
	v_mfma_f32_16x16x32_bf16 v[108:111], v[252:255], v[156:159], v[108:111]
	v_mfma_f32_16x16x32_bf16 v[76:79], v[252:255], v[138:141], v[76:79]
	s_waitcnt lgkmcnt(6)
	v_mfma_f32_16x16x32_bf16 v[112:115], v[232:235], v[210:213], v[112:115]
	v_mfma_f32_16x16x32_bf16 v[80:83], v[232:235], v[214:217], v[80:83]
	s_waitcnt lgkmcnt(4)
	v_mfma_f32_16x16x32_bf16 v[112:115], v[236:239], v[156:159], v[112:115]
	v_mfma_f32_16x16x32_bf16 v[80:83], v[236:239], v[138:141], v[80:83]
	s_waitcnt lgkmcnt(2)
	v_mfma_f32_16x16x32_bf16 v[116:119], v[240:243], v[210:213], v[116:119]
	v_mfma_f32_16x16x32_bf16 v[84:87], v[240:243], v[214:217], v[84:87]
	s_waitcnt lgkmcnt(0)
	v_mfma_f32_16x16x32_bf16 v[116:119], v[244:247], v[156:159], v[116:119]
	v_mfma_f32_16x16x32_bf16 v[84:87], v[244:247], v[138:141], v[84:87]
